# v18 with the designated early L2 write-back after P1 delayed by ~12us (3 x s_sleep 127) so it covers more of the phase output
# speedup vs baseline: 1.0021x; 1.0021x over previous
.LBB0_617:
	s_waitcnt vmcnt(0)
	s_waitcnt vmcnt(0)
	s_barrier
	s_mov_b64 s[0:1], exec
	v_readlane_b32 s8, v245, 16
	v_readlane_b32 s9, v245, 17
	v_readlane_b32 s22, v244, 19
	s_and_b64 s[8:9], s[0:1], s[8:9]
	v_readlane_b32 s23, v244, 20
	s_mov_b64 exec, s[8:9]
	s_cbranch_execz .LBB0_669
	s_cmp_lt_u32 s2, 0xf8
	s_cbranch_scc1 .Lwb1_skip0
	s_sleep 127
	s_sleep 127
	s_sleep 127
	buffer_wbl2 sc1
	s_waitcnt vmcnt(0)
